# weight transposes for MLP and layer-1 weights deferred from the prologue into idle tails of in-proj and MLP-up phases
# speedup vs baseline: 1.0170x; 1.0170x over previous
.LBB0_19:
	s_lshl_b32 s0, s2, 3
	s_add_i32 s10, s14, s0
	s_cmp_gt_i32 s10, 0x16bf
	s_cbranch_scc1 .LBB0_42
	s_lshl_b32 s11, s34, 3
	s_add_u32 s12, s64, 0x100000
	s_addc_u32 s13, s65, 0
	s_lshl_b32 s0, s14, 14
	v_lshrrev_b32_e32 v6, 5, v43
	v_and_b32_e32 v2, 31, v2
	s_add_i32 s0, s0, 0
	v_lshlrev_b32_e32 v4, 2, v2
	v_mul_u32_u24_e32 v5, 0x84, v6
	v_add3_u32 v7, s0, v4, v5
	v_lshlrev_b32_e32 v4, 3, v43
	v_lshrrev_b32_e32 v8, 3, v43
	v_and_b32_e32 v4, 56, v4
	v_mul_u32_u24_e32 v5, 0x84, v4
	v_lshlrev_b32_e32 v9, 2, v8
	v_mov_b32_e32 v3, 0
	v_add3_u32 v9, s0, v5, v9
	v_or_b32_e32 v10, 8, v8
	v_or_b32_e32 v11, 16, v8
	v_or_b32_e32 v12, 24, v8
	s_lshl_b32 s14, s10, 5
	s_lshl_b32 s15, s34, 8
	s_movk_i32 s16, 0x4000
	s_mov_b32 s17, 0x8000
	s_mov_b32 s18, 0xc000
	s_mov_b32 s19, 0x10000
	s_mov_b32 s20, 0x14000
	s_mov_b32 s21, 0x18000
	s_mov_b32 s22, 0x1c000
	s_mov_b32 s23, 0x20000
	s_mov_b32 s24, 0x24000
	s_mov_b32 s25, 0x28000
	s_mov_b32 s26, 0x2c000
	s_mov_b32 s27, 0x30000
	s_mov_b32 s28, 0x34000
	s_mov_b32 s29, 0x38000
	s_mov_b32 s30, 0x3c000
	s_mov_b32 s31, 0x40000
	s_mov_b32 s36, 0x44000
	s_mov_b32 s37, 0x48000
	s_mov_b32 s38, 0x4c000
	s_mov_b32 s39, 0x50000
	s_mov_b32 s40, 0x54000
	s_mov_b32 s41, 0x58000
	s_mov_b32 s42, 0x5c000
	s_mov_b32 s43, 0x60000
	s_mov_b32 s44, 0x64000
	s_mov_b32 s45, 0x68000
	s_mov_b32 s46, 0x6c000
	s_mov_b32 s47, 0x70000
	s_mov_b32 s48, 0x74000
	s_mov_b32 s49, 0x78000
	s_mov_b32 s50, 0x7c000
	s_mov_b32 s51, 0x21000
	v_lshlrev_b32_e32 v2, 2, v2
	v_add_u32_e32 v13, 0x400, v7
	v_add_u32_e32 v14, 0x800, v7
	v_add_u32_e32 v15, 0xc00, v7
	v_add_u32_e32 v16, 0x1000, v7
	v_add_u32_e32 v17, 0x1400, v7
	v_add_u32_e32 v18, 0x1800, v7
	v_add_u32_e32 v19, 0x1c00, v7
	v_lshlrev_b32_e32 v4, 1, v4
	s_mov_b32 s52, 0x27000
	s_mov_b32 s53, 0x2d000
	s_mov_b32 s54, 0x4e000
	s_mov_b32 s55, 0x5a000
	s_branch .LBB0_22
.LBB0_21:
	s_add_i32 s10, s10, s11
	s_add_i32 s14, s14, s15
	s_cmp_gt_i32 s10, 0x16bf
	s_cbranch_scc1 .LBB0_42

.LBB0_298:
	s_cmp_lt_u32 s2, 48
	s_cbranch_scc1 .Ltr_a_done
	s_lshl_b32 vcc_lo, s3, 10
	s_mov_b32 vcc_hi, m0
	s_mov_b32 m0, vcc_lo
	s_nop 0
	ds_write_addtid_b32 v0 offset:0
	ds_write_addtid_b32 v1 offset:256
	ds_write_addtid_b32 v2 offset:512
	ds_write_addtid_b32 v3 offset:768
	s_waitcnt lgkmcnt(0)
	v_mbcnt_lo_u32_b32 v2, -1, 0
	v_mbcnt_hi_u32_b32 v2, -1, v2
	s_mul_i32 vcc_lo, s3, 13312
	s_add_i32 vcc_lo, vcc_lo, 8192
	v_lshl_add_u32 v0, v2, 4, vcc_lo
	ds_write_b128 v0, v[4:7]
	ds_write_b128 v0, v[8:11] offset:1024
	ds_write_b128 v0, v[12:15] offset:2048
	ds_write_b128 v0, v[16:19] offset:3072
	ds_write_b128 v0, v[20:23] offset:4096
	ds_write_b128 v0, v[24:27] offset:5120
	ds_write_b128 v0, v[28:31] offset:6144
	ds_write_b128 v0, v[32:35] offset:7168
	ds_write_b128 v0, v[36:39] offset:8192
	ds_write_b128 v0, v[40:43] offset:9216
	ds_write_b128 v0, v[44:47] offset:10240
	ds_write_b128 v0, v[48:51] offset:11264
	ds_write_b128 v0, v[52:55] offset:12288
	s_waitcnt lgkmcnt(0)
	v_writelane_b32 v1, s60, 0
	v_writelane_b32 v1, s61, 1
	v_writelane_b32 v1, s62, 2
	v_writelane_b32 v1, s63, 3
	v_writelane_b32 v1, s64, 4
	v_writelane_b32 v1, s65, 5
	v_writelane_b32 v1, s66, 6
	v_writelane_b32 v1, s67, 7
	v_writelane_b32 v1, s68, 8
	v_writelane_b32 v1, s69, 9
	v_writelane_b32 v1, s70, 10
	v_writelane_b32 v1, s71, 11
	v_writelane_b32 v1, s72, 12
	v_writelane_b32 v1, s73, 13
	v_writelane_b32 v1, s74, 14
	v_writelane_b32 v1, s75, 15
	v_writelane_b32 v1, s76, 16
	v_writelane_b32 v1, s77, 17
	v_writelane_b32 v1, s78, 18
	v_writelane_b32 v1, s79, 19
	v_writelane_b32 v1, s80, 20
	v_writelane_b32 v1, s81, 21
	v_writelane_b32 v1, s82, 22
	v_writelane_b32 v1, s83, 23
	v_writelane_b32 v1, vcc_hi, 24
	v_mov_b32_e32 v53, v2
	v_and_b32_e32 v54, 31, v53
	v_lshrrev_b32_e32 v55, 5, v53
	v_readlane_b32 s76, v248, 0
	v_readlane_b32 s77, v248, 1
	s_nop 3
	s_sub_u32 s76, s76, 0xd0
	s_subb_u32 s77, s77, 0
	s_sub_u32 s63, s2, 48
	s_lshl_b32 s63, s63, 3
	s_add_u32 s63, s63, s3
	s_sub_u32 s62, s34, 48
	s_lshl_b32 s62, s62, 3
	s_cmp_ge_i32 s44, 11
	s_cselect_b32 s81, 1, 0
	s_load_dwordx2 s[82:83], s[76:77], 0xc0
	s_load_dwordx2 s[64:65], s[76:77], 0xa0
	s_waitcnt lgkmcnt(0)
	s_mul_i32 s69, s81, 0x4000000
	s_add_u32 s64, s64, s69
	s_addc_u32 s65, s65, 0
	s_mul_i32 s69, s81, 0x5780000
	s_add_u32 s69, s69, 0x1880000
	s_add_u32 s66, s82, s69
	s_addc_u32 s67, s83, 0
	s_mov_b32 s68, 0x10000
	s_mov_b32 s61, 8192
	s_mov_b32 s60, s63
	v_mov_b32_e32 v2, 0x2000
	v_mul_u32_u24_e32 v2, v2, v55
	v_add_lshl_u32 v2, v2, v54, 2
	v_mov_b32_e32 v52, 0x1000
	v_mul_u32_u24_e32 v52, v52, v54
	v_lshl_add_u32 v52, v55, 6, v52
.Ltr_a_m0_loop:
	s_cmp_ge_u32 s60, s61
	s_cbranch_scc1 .Ltr_a_m0_end
	s_and_b32 s71, s60, 255
	s_lshr_b32 s70, s60, 8
	s_mul_i32 s69, s70, 0x200000
	s_lshl_b32 s80, s71, 7
	s_add_u32 s69, s69, s80
	s_add_u32 s72, s64, s69
	s_addc_u32 s73, s65, 0
	s_mul_i32 s69, s71, 0x20000
	s_lshl_b32 s80, s70, 7
	s_add_u32 s69, s69, s80
	s_add_u32 s74, s66, s69
	s_addc_u32 s75, s67, 0
	v_mov_b32_e32 v3, v2
	global_load_dword v4, v3, s[72:73]
	v_add_u32_e32 v3, s68, v3
	global_load_dword v5, v3, s[72:73]
	v_add_u32_e32 v3, s68, v3
	global_load_dword v6, v3, s[72:73]
	v_add_u32_e32 v3, s68, v3
	global_load_dword v7, v3, s[72:73]
	v_add_u32_e32 v3, s68, v3
	global_load_dword v8, v3, s[72:73]
	v_add_u32_e32 v3, s68, v3
	global_load_dword v9, v3, s[72:73]
	v_add_u32_e32 v3, s68, v3
	global_load_dword v10, v3, s[72:73]
	v_add_u32_e32 v3, s68, v3
	global_load_dword v11, v3, s[72:73]
	v_add_u32_e32 v3, s68, v3
	global_load_dword v12, v3, s[72:73]
	v_add_u32_e32 v3, s68, v3
	global_load_dword v13, v3, s[72:73]
	v_add_u32_e32 v3, s68, v3
	global_load_dword v14, v3, s[72:73]
	v_add_u32_e32 v3, s68, v3
	global_load_dword v15, v3, s[72:73]
	v_add_u32_e32 v3, s68, v3
	global_load_dword v16, v3, s[72:73]
	v_add_u32_e32 v3, s68, v3
	global_load_dword v17, v3, s[72:73]
	v_add_u32_e32 v3, s68, v3
	global_load_dword v18, v3, s[72:73]
	v_add_u32_e32 v3, s68, v3
	global_load_dword v19, v3, s[72:73]
	v_add_u32_e32 v3, s68, v3
	global_load_dword v20, v3, s[72:73]
	v_add_u32_e32 v3, s68, v3
	global_load_dword v21, v3, s[72:73]
	v_add_u32_e32 v3, s68, v3
	global_load_dword v22, v3, s[72:73]
	v_add_u32_e32 v3, s68, v3
	global_load_dword v23, v3, s[72:73]
	v_add_u32_e32 v3, s68, v3
	global_load_dword v24, v3, s[72:73]
	v_add_u32_e32 v3, s68, v3
	global_load_dword v25, v3, s[72:73]
	v_add_u32_e32 v3, s68, v3
	global_load_dword v26, v3, s[72:73]
	v_add_u32_e32 v3, s68, v3
	global_load_dword v27, v3, s[72:73]
	v_add_u32_e32 v3, s68, v3
	global_load_dword v28, v3, s[72:73]
	v_add_u32_e32 v3, s68, v3
	global_load_dword v29, v3, s[72:73]
	v_add_u32_e32 v3, s68, v3
	global_load_dword v30, v3, s[72:73]
	v_add_u32_e32 v3, s68, v3
	global_load_dword v31, v3, s[72:73]
	v_add_u32_e32 v3, s68, v3
	global_load_dword v32, v3, s[72:73]
	v_add_u32_e32 v3, s68, v3
	global_load_dword v33, v3, s[72:73]
	v_add_u32_e32 v3, s68, v3
	global_load_dword v34, v3, s[72:73]
	v_add_u32_e32 v3, s68, v3
	global_load_dword v35, v3, s[72:73]
	s_waitcnt vmcnt(0)
	v_permlane32_swap_b32_e32 v4, v20
	v_permlane32_swap_b32_e32 v5, v21
	v_permlane32_swap_b32_e32 v6, v22
	v_permlane32_swap_b32_e32 v7, v23
	v_permlane32_swap_b32_e32 v8, v24
	v_permlane32_swap_b32_e32 v9, v25
	v_permlane32_swap_b32_e32 v10, v26
	v_permlane32_swap_b32_e32 v11, v27
	v_permlane32_swap_b32_e32 v12, v28
	v_permlane32_swap_b32_e32 v13, v29
	v_permlane32_swap_b32_e32 v14, v30
	v_permlane32_swap_b32_e32 v15, v31
	v_permlane32_swap_b32_e32 v16, v32
	v_permlane32_swap_b32_e32 v17, v33
	v_permlane32_swap_b32_e32 v18, v34
	v_permlane32_swap_b32_e32 v19, v35
	v_cvt_pk_bf16_f32 v36, v4, v20
	v_cvt_pk_bf16_f32 v37, v5, v21
	v_cvt_pk_bf16_f32 v38, v6, v22
	v_cvt_pk_bf16_f32 v39, v7, v23
	v_cvt_pk_bf16_f32 v40, v8, v24
	v_cvt_pk_bf16_f32 v41, v9, v25
	v_cvt_pk_bf16_f32 v42, v10, v26
	v_cvt_pk_bf16_f32 v43, v11, v27
	v_cvt_pk_bf16_f32 v44, v12, v28
	v_cvt_pk_bf16_f32 v45, v13, v29
	v_cvt_pk_bf16_f32 v46, v14, v30
	v_cvt_pk_bf16_f32 v47, v15, v31
	v_cvt_pk_bf16_f32 v48, v16, v32
	v_cvt_pk_bf16_f32 v49, v17, v33
	v_cvt_pk_bf16_f32 v50, v18, v34
	v_cvt_pk_bf16_f32 v51, v19, v35
	global_store_dwordx4 v52, v[36:39], s[74:75]
	global_store_dwordx4 v52, v[40:43], s[74:75] offset:16
	global_store_dwordx4 v52, v[44:47], s[74:75] offset:32
	global_store_dwordx4 v52, v[48:51], s[74:75] offset:48
	s_add_u32 s60, s60, s62
	s_branch .Ltr_a_m0_loop
.Ltr_a_m0_end:
	s_load_dwordx2 s[64:65], s[76:77], 0xa8
	s_waitcnt lgkmcnt(0)
	s_mul_i32 s69, s81, 0x4000000
	s_add_u32 s64, s64, s69
	s_addc_u32 s65, s65, 0
	s_mul_i32 s69, s81, 0x5780000
	s_add_u32 s69, s69, 0x3880000
	s_add_u32 s66, s82, s69
	s_addc_u32 s67, s83, 0
	s_mov_b32 s68, 0x4000
	s_mov_b32 s61, 8192
	s_mov_b32 s60, s63
	v_mov_b32_e32 v2, 0x800
	v_mul_u32_u24_e32 v2, v2, v55
	v_add_lshl_u32 v2, v2, v54, 2
	v_mov_b32_e32 v52, 0x4000
	v_mul_u32_u24_e32 v52, v52, v54
	v_lshl_add_u32 v52, v55, 6, v52
.Ltr_a_m1_loop:
	s_cmp_ge_u32 s60, s61
	s_cbranch_scc1 .Ltr_a_m1_end
	s_and_b32 s71, s60, 63
	s_lshr_b32 s70, s60, 6
	s_mul_i32 s69, s70, 0x80000
	s_lshl_b32 s80, s71, 7
	s_add_u32 s69, s69, s80
	s_add_u32 s72, s64, s69
	s_addc_u32 s73, s65, 0
	s_mul_i32 s69, s71, 0x80000
	s_lshl_b32 s80, s70, 7
	s_add_u32 s69, s69, s80
	s_add_u32 s74, s66, s69
	s_addc_u32 s75, s67, 0
	v_mov_b32_e32 v3, v2
	global_load_dword v4, v3, s[72:73]
	v_add_u32_e32 v3, s68, v3
	global_load_dword v5, v3, s[72:73]
	v_add_u32_e32 v3, s68, v3
	global_load_dword v6, v3, s[72:73]
	v_add_u32_e32 v3, s68, v3
	global_load_dword v7, v3, s[72:73]
	v_add_u32_e32 v3, s68, v3
	global_load_dword v8, v3, s[72:73]
	v_add_u32_e32 v3, s68, v3
	global_load_dword v9, v3, s[72:73]
	v_add_u32_e32 v3, s68, v3
	global_load_dword v10, v3, s[72:73]
	v_add_u32_e32 v3, s68, v3
	global_load_dword v11, v3, s[72:73]
	v_add_u32_e32 v3, s68, v3
	global_load_dword v12, v3, s[72:73]
	v_add_u32_e32 v3, s68, v3
	global_load_dword v13, v3, s[72:73]
	v_add_u32_e32 v3, s68, v3
	global_load_dword v14, v3, s[72:73]
	v_add_u32_e32 v3, s68, v3
	global_load_dword v15, v3, s[72:73]
	v_add_u32_e32 v3, s68, v3
	global_load_dword v16, v3, s[72:73]
	v_add_u32_e32 v3, s68, v3
	global_load_dword v17, v3, s[72:73]
	v_add_u32_e32 v3, s68, v3
	global_load_dword v18, v3, s[72:73]
	v_add_u32_e32 v3, s68, v3
	global_load_dword v19, v3, s[72:73]
	v_add_u32_e32 v3, s68, v3
	global_load_dword v20, v3, s[72:73]
	v_add_u32_e32 v3, s68, v3
	global_load_dword v21, v3, s[72:73]
	v_add_u32_e32 v3, s68, v3
	global_load_dword v22, v3, s[72:73]
	v_add_u32_e32 v3, s68, v3
	global_load_dword v23, v3, s[72:73]
	v_add_u32_e32 v3, s68, v3
	global_load_dword v24, v3, s[72:73]
	v_add_u32_e32 v3, s68, v3
	global_load_dword v25, v3, s[72:73]
	v_add_u32_e32 v3, s68, v3
	global_load_dword v26, v3, s[72:73]
	v_add_u32_e32 v3, s68, v3
	global_load_dword v27, v3, s[72:73]
	v_add_u32_e32 v3, s68, v3
	global_load_dword v28, v3, s[72:73]
	v_add_u32_e32 v3, s68, v3
	global_load_dword v29, v3, s[72:73]
	v_add_u32_e32 v3, s68, v3
	global_load_dword v30, v3, s[72:73]
	v_add_u32_e32 v3, s68, v3
	global_load_dword v31, v3, s[72:73]
	v_add_u32_e32 v3, s68, v3
	global_load_dword v32, v3, s[72:73]
	v_add_u32_e32 v3, s68, v3
	global_load_dword v33, v3, s[72:73]
	v_add_u32_e32 v3, s68, v3
	global_load_dword v34, v3, s[72:73]
	v_add_u32_e32 v3, s68, v3
	global_load_dword v35, v3, s[72:73]
	s_waitcnt vmcnt(0)
	v_permlane32_swap_b32_e32 v4, v20
	v_permlane32_swap_b32_e32 v5, v21
	v_permlane32_swap_b32_e32 v6, v22
	v_permlane32_swap_b32_e32 v7, v23
	v_permlane32_swap_b32_e32 v8, v24
	v_permlane32_swap_b32_e32 v9, v25
	v_permlane32_swap_b32_e32 v10, v26
	v_permlane32_swap_b32_e32 v11, v27
	v_permlane32_swap_b32_e32 v12, v28
	v_permlane32_swap_b32_e32 v13, v29
	v_permlane32_swap_b32_e32 v14, v30
	v_permlane32_swap_b32_e32 v15, v31
	v_permlane32_swap_b32_e32 v16, v32
	v_permlane32_swap_b32_e32 v17, v33
	v_permlane32_swap_b32_e32 v18, v34
	v_permlane32_swap_b32_e32 v19, v35
	v_cvt_pk_bf16_f32 v36, v4, v20
	v_cvt_pk_bf16_f32 v37, v5, v21
	v_cvt_pk_bf16_f32 v38, v6, v22
	v_cvt_pk_bf16_f32 v39, v7, v23
	v_cvt_pk_bf16_f32 v40, v8, v24
	v_cvt_pk_bf16_f32 v41, v9, v25
	v_cvt_pk_bf16_f32 v42, v10, v26
	v_cvt_pk_bf16_f32 v43, v11, v27
	v_cvt_pk_bf16_f32 v44, v12, v28
	v_cvt_pk_bf16_f32 v45, v13, v29
	v_cvt_pk_bf16_f32 v46, v14, v30
	v_cvt_pk_bf16_f32 v47, v15, v31
	v_cvt_pk_bf16_f32 v48, v16, v32
	v_cvt_pk_bf16_f32 v49, v17, v33
	v_cvt_pk_bf16_f32 v50, v18, v34
	v_cvt_pk_bf16_f32 v51, v19, v35
	global_store_dwordx4 v52, v[36:39], s[74:75]
	global_store_dwordx4 v52, v[40:43], s[74:75] offset:16
	global_store_dwordx4 v52, v[44:47], s[74:75] offset:32
	global_store_dwordx4 v52, v[48:51], s[74:75] offset:48
	s_add_u32 s60, s60, s62
	s_branch .Ltr_a_m1_loop
.Ltr_a_m1_end:
	v_readlane_b32 vcc_hi, v1, 24
	v_readlane_b32 s60, v1, 0
	v_readlane_b32 s61, v1, 1
	v_readlane_b32 s62, v1, 2
	v_readlane_b32 s63, v1, 3
	v_readlane_b32 s64, v1, 4
	v_readlane_b32 s65, v1, 5
	v_readlane_b32 s66, v1, 6
	v_readlane_b32 s67, v1, 7
	v_readlane_b32 s68, v1, 8
	v_readlane_b32 s69, v1, 9
	v_readlane_b32 s70, v1, 10
	v_readlane_b32 s71, v1, 11
	v_readlane_b32 s72, v1, 12
	v_readlane_b32 s73, v1, 13
	v_readlane_b32 s74, v1, 14
	v_readlane_b32 s75, v1, 15
	v_readlane_b32 s76, v1, 16
	v_readlane_b32 s77, v1, 17
	v_readlane_b32 s78, v1, 18
	v_readlane_b32 s79, v1, 19
	v_readlane_b32 s80, v1, 20
	v_readlane_b32 s81, v1, 21
	v_readlane_b32 s82, v1, 22
	v_readlane_b32 s83, v1, 23
	ds_read_b128 v[4:7], v0
	ds_read_b128 v[8:11], v0 offset:1024
	ds_read_b128 v[12:15], v0 offset:2048
	ds_read_b128 v[16:19], v0 offset:3072
	ds_read_b128 v[20:23], v0 offset:4096
	ds_read_b128 v[24:27], v0 offset:5120
	ds_read_b128 v[28:31], v0 offset:6144
	ds_read_b128 v[32:35], v0 offset:7168
	ds_read_b128 v[36:39], v0 offset:8192
	ds_read_b128 v[40:43], v0 offset:9216
	ds_read_b128 v[44:47], v0 offset:10240
	ds_read_b128 v[48:51], v0 offset:11264
	ds_read_b128 v[52:55], v0 offset:12288
	s_lshl_b32 vcc_lo, s3, 10
	s_mov_b32 m0, vcc_lo
	s_nop 0
	ds_read_addtid_b32 v0 offset:0
	ds_read_addtid_b32 v1 offset:256
	ds_read_addtid_b32 v2 offset:512
	ds_read_addtid_b32 v3 offset:768
	s_waitcnt lgkmcnt(0)
	s_mov_b32 m0, vcc_hi

.LBB0_1147:
	s_cmp_lt_u32 s2, 128
	s_cbranch_scc1 .Ltr_b_done
	s_cmp_ge_i32 s44, 11
	s_cbranch_scc1 .Ltr_b_done
	s_lshl_b32 vcc_lo, s3, 10
	s_mov_b32 vcc_hi, m0
	s_mov_b32 m0, vcc_lo
	s_nop 0
	ds_write_addtid_b32 v0 offset:0
	ds_write_addtid_b32 v1 offset:256
	ds_write_addtid_b32 v2 offset:512
	ds_write_addtid_b32 v3 offset:768
	s_waitcnt lgkmcnt(0)
	v_mbcnt_lo_u32_b32 v2, -1, 0
	v_mbcnt_hi_u32_b32 v2, -1, v2
	s_mul_i32 vcc_lo, s3, 13312
	s_add_i32 vcc_lo, vcc_lo, 8192
	v_lshl_add_u32 v0, v2, 4, vcc_lo
	ds_write_b128 v0, v[4:7]
	ds_write_b128 v0, v[8:11] offset:1024
	ds_write_b128 v0, v[12:15] offset:2048
	ds_write_b128 v0, v[16:19] offset:3072
	ds_write_b128 v0, v[20:23] offset:4096
	ds_write_b128 v0, v[24:27] offset:5120
	ds_write_b128 v0, v[28:31] offset:6144
	ds_write_b128 v0, v[32:35] offset:7168
	ds_write_b128 v0, v[36:39] offset:8192
	ds_write_b128 v0, v[40:43] offset:9216
	ds_write_b128 v0, v[44:47] offset:10240
	ds_write_b128 v0, v[48:51] offset:11264
	ds_write_b128 v0, v[52:55] offset:12288
	s_waitcnt lgkmcnt(0)
	v_writelane_b32 v1, s60, 0
	v_writelane_b32 v1, s61, 1
	v_writelane_b32 v1, s62, 2
	v_writelane_b32 v1, s63, 3
	v_writelane_b32 v1, s64, 4
	v_writelane_b32 v1, s65, 5
	v_writelane_b32 v1, s66, 6
	v_writelane_b32 v1, s67, 7
	v_writelane_b32 v1, s68, 8
	v_writelane_b32 v1, s69, 9
	v_writelane_b32 v1, s70, 10
	v_writelane_b32 v1, s71, 11
	v_writelane_b32 v1, s72, 12
	v_writelane_b32 v1, s73, 13
	v_writelane_b32 v1, s74, 14
	v_writelane_b32 v1, s75, 15
	v_writelane_b32 v1, s76, 16
	v_writelane_b32 v1, s77, 17
	v_writelane_b32 v1, s78, 18
	v_writelane_b32 v1, s79, 19
	v_writelane_b32 v1, s80, 20
	v_writelane_b32 v1, s81, 21
	v_writelane_b32 v1, s82, 22
	v_writelane_b32 v1, s83, 23
	v_writelane_b32 v1, vcc_hi, 24
	v_mov_b32_e32 v53, v2
	v_and_b32_e32 v54, 31, v53
	v_lshrrev_b32_e32 v55, 5, v53
	v_readlane_b32 s76, v248, 0
	v_readlane_b32 s77, v248, 1
	s_nop 3
	s_sub_u32 s76, s76, 0xd0
	s_subb_u32 s77, s77, 0
	s_sub_u32 s63, s2, 128
	s_lshl_b32 s63, s63, 3
	s_add_u32 s63, s63, s3
	s_sub_u32 s62, s34, 128
	s_lshl_b32 s62, s62, 3
	s_load_dwordx2 s[82:83], s[76:77], 0xc0
	s_load_dwordx2 s[64:65], s[76:77], 0x40
	s_waitcnt lgkmcnt(0)
	s_add_u32 s64, s64, 0x1680000
	s_addc_u32 s65, s65, 0
	s_mov_b32 s69, 0x5880000
	s_add_u32 s66, s82, s69
	s_addc_u32 s67, s83, 0
	s_mov_b32 s68, 0x5a00
	s_mov_b32 s61, 2880
	s_mov_b32 s60, s63
	v_mov_b32_e32 v2, 0xb40
	v_mul_u32_u24_e32 v2, v2, v55
	v_add_lshl_u32 v2, v2, v54, 2
	v_mov_b32_e32 v52, 0x1000
	v_mul_u32_u24_e32 v52, v52, v54
	v_lshl_add_u32 v52, v55, 6, v52
.Ltr_b_m0_loop:
	s_cmp_ge_u32 s60, s61
	s_cbranch_scc1 .Ltr_b_m0_end
	s_mul_i32 s70, s60, 2913
	s_lshr_b32 s70, s70, 18
	s_mul_i32 s69, s70, 90
	s_sub_u32 s71, s60, s69
	s_mul_i32 s69, s70, 0xb4000
	s_lshl_b32 s80, s71, 7
	s_add_u32 s69, s69, s80
	s_add_u32 s72, s64, s69
	s_addc_u32 s73, s65, 0
	s_mul_i32 s69, s71, 0x20000
	s_lshl_b32 s80, s70, 7
	s_add_u32 s69, s69, s80
	s_add_u32 s74, s66, s69
	s_addc_u32 s75, s67, 0
	v_mov_b32_e32 v3, v2
	global_load_dword v4, v3, s[72:73]
	v_add_u32_e32 v3, s68, v3
	global_load_dword v5, v3, s[72:73]
	v_add_u32_e32 v3, s68, v3
	global_load_dword v6, v3, s[72:73]
	v_add_u32_e32 v3, s68, v3
	global_load_dword v7, v3, s[72:73]
	v_add_u32_e32 v3, s68, v3
	global_load_dword v8, v3, s[72:73]
	v_add_u32_e32 v3, s68, v3
	global_load_dword v9, v3, s[72:73]
	v_add_u32_e32 v3, s68, v3
	global_load_dword v10, v3, s[72:73]
	v_add_u32_e32 v3, s68, v3
	global_load_dword v11, v3, s[72:73]
	v_add_u32_e32 v3, s68, v3
	global_load_dword v12, v3, s[72:73]
	v_add_u32_e32 v3, s68, v3
	global_load_dword v13, v3, s[72:73]
	v_add_u32_e32 v3, s68, v3
	global_load_dword v14, v3, s[72:73]
	v_add_u32_e32 v3, s68, v3
	global_load_dword v15, v3, s[72:73]
	v_add_u32_e32 v3, s68, v3
	global_load_dword v16, v3, s[72:73]
	v_add_u32_e32 v3, s68, v3
	global_load_dword v17, v3, s[72:73]
	v_add_u32_e32 v3, s68, v3
	global_load_dword v18, v3, s[72:73]
	v_add_u32_e32 v3, s68, v3
	global_load_dword v19, v3, s[72:73]
	v_add_u32_e32 v3, s68, v3
	global_load_dword v20, v3, s[72:73]
	v_add_u32_e32 v3, s68, v3
	global_load_dword v21, v3, s[72:73]
	v_add_u32_e32 v3, s68, v3
	global_load_dword v22, v3, s[72:73]
	v_add_u32_e32 v3, s68, v3
	global_load_dword v23, v3, s[72:73]
	v_add_u32_e32 v3, s68, v3
	global_load_dword v24, v3, s[72:73]
	v_add_u32_e32 v3, s68, v3
	global_load_dword v25, v3, s[72:73]
	v_add_u32_e32 v3, s68, v3
	global_load_dword v26, v3, s[72:73]
	v_add_u32_e32 v3, s68, v3
	global_load_dword v27, v3, s[72:73]
	v_add_u32_e32 v3, s68, v3
	global_load_dword v28, v3, s[72:73]
	v_add_u32_e32 v3, s68, v3
	global_load_dword v29, v3, s[72:73]
	v_add_u32_e32 v3, s68, v3
	global_load_dword v30, v3, s[72:73]
	v_add_u32_e32 v3, s68, v3
	global_load_dword v31, v3, s[72:73]
	v_add_u32_e32 v3, s68, v3
	global_load_dword v32, v3, s[72:73]
	v_add_u32_e32 v3, s68, v3
	global_load_dword v33, v3, s[72:73]
	v_add_u32_e32 v3, s68, v3
	global_load_dword v34, v3, s[72:73]
	v_add_u32_e32 v3, s68, v3
	global_load_dword v35, v3, s[72:73]
	s_waitcnt vmcnt(0)
	v_permlane32_swap_b32_e32 v4, v20
	v_permlane32_swap_b32_e32 v5, v21
	v_permlane32_swap_b32_e32 v6, v22
	v_permlane32_swap_b32_e32 v7, v23
	v_permlane32_swap_b32_e32 v8, v24
	v_permlane32_swap_b32_e32 v9, v25
	v_permlane32_swap_b32_e32 v10, v26
	v_permlane32_swap_b32_e32 v11, v27
	v_permlane32_swap_b32_e32 v12, v28
	v_permlane32_swap_b32_e32 v13, v29
	v_permlane32_swap_b32_e32 v14, v30
	v_permlane32_swap_b32_e32 v15, v31
	v_permlane32_swap_b32_e32 v16, v32
	v_permlane32_swap_b32_e32 v17, v33
	v_permlane32_swap_b32_e32 v18, v34
	v_permlane32_swap_b32_e32 v19, v35
	v_cvt_pk_bf16_f32 v36, v4, v20
	v_cvt_pk_bf16_f32 v37, v5, v21
	v_cvt_pk_bf16_f32 v38, v6, v22
	v_cvt_pk_bf16_f32 v39, v7, v23
	v_cvt_pk_bf16_f32 v40, v8, v24
	v_cvt_pk_bf16_f32 v41, v9, v25
	v_cvt_pk_bf16_f32 v42, v10, v26
	v_cvt_pk_bf16_f32 v43, v11, v27
	v_cvt_pk_bf16_f32 v44, v12, v28
	v_cvt_pk_bf16_f32 v45, v13, v29
	v_cvt_pk_bf16_f32 v46, v14, v30
	v_cvt_pk_bf16_f32 v47, v15, v31
	v_cvt_pk_bf16_f32 v48, v16, v32
	v_cvt_pk_bf16_f32 v49, v17, v33
	v_cvt_pk_bf16_f32 v50, v18, v34
	v_cvt_pk_bf16_f32 v51, v19, v35
	global_store_dwordx4 v52, v[36:39], s[74:75]
	global_store_dwordx4 v52, v[40:43], s[74:75] offset:16
	global_store_dwordx4 v52, v[44:47], s[74:75] offset:32
	global_store_dwordx4 v52, v[48:51], s[74:75] offset:48
	s_add_u32 s60, s60, s62
	s_branch .Ltr_b_m0_loop
.Ltr_b_m0_end:
	s_load_dwordx2 s[64:65], s[76:77], 0x50
	s_waitcnt lgkmcnt(0)
	s_add_u32 s64, s64, 0x300000
	s_addc_u32 s65, s65, 0
	s_mov_b32 s69, 0x6480000
	s_add_u32 s66, s82, s69
	s_addc_u32 s67, s83, 0
	s_mov_b32 s68, 0x3000
	s_mov_b32 s61, 384
	s_mov_b32 s60, s63
	v_mov_b32_e32 v2, 0x600
	v_mul_u32_u24_e32 v2, v2, v55
	v_add_lshl_u32 v2, v2, v54, 2
	v_mov_b32_e32 v52, 0x400
	v_mul_u32_u24_e32 v52, v52, v54
	v_lshl_add_u32 v52, v55, 6, v52
.Ltr_b_m1_loop:
	s_cmp_ge_u32 s60, s61
	s_cbranch_scc1 .Ltr_b_m1_end
	s_mul_i32 s70, s60, 1366
	s_lshr_b32 s70, s70, 16
	s_mul_i32 s69, s70, 48
	s_sub_u32 s71, s60, s69
	s_mul_i32 s69, s70, 0x60000
	s_lshl_b32 s80, s71, 7
	s_add_u32 s69, s69, s80
	s_add_u32 s72, s64, s69
	s_addc_u32 s73, s65, 0
	s_mul_i32 s69, s71, 0x8000
	s_lshl_b32 s80, s70, 7
	s_add_u32 s69, s69, s80
	s_add_u32 s74, s66, s69
	s_addc_u32 s75, s67, 0
	v_mov_b32_e32 v3, v2
	global_load_dword v4, v3, s[72:73]
	v_add_u32_e32 v3, s68, v3
	global_load_dword v5, v3, s[72:73]
	v_add_u32_e32 v3, s68, v3
	global_load_dword v6, v3, s[72:73]
	v_add_u32_e32 v3, s68, v3
	global_load_dword v7, v3, s[72:73]
	v_add_u32_e32 v3, s68, v3
	global_load_dword v8, v3, s[72:73]
	v_add_u32_e32 v3, s68, v3
	global_load_dword v9, v3, s[72:73]
	v_add_u32_e32 v3, s68, v3
	global_load_dword v10, v3, s[72:73]
	v_add_u32_e32 v3, s68, v3
	global_load_dword v11, v3, s[72:73]
	v_add_u32_e32 v3, s68, v3
	global_load_dword v12, v3, s[72:73]
	v_add_u32_e32 v3, s68, v3
	global_load_dword v13, v3, s[72:73]
	v_add_u32_e32 v3, s68, v3
	global_load_dword v14, v3, s[72:73]
	v_add_u32_e32 v3, s68, v3
	global_load_dword v15, v3, s[72:73]
	v_add_u32_e32 v3, s68, v3
	global_load_dword v16, v3, s[72:73]
	v_add_u32_e32 v3, s68, v3
	global_load_dword v17, v3, s[72:73]
	v_add_u32_e32 v3, s68, v3
	global_load_dword v18, v3, s[72:73]
	v_add_u32_e32 v3, s68, v3
	global_load_dword v19, v3, s[72:73]
	v_add_u32_e32 v3, s68, v3
	global_load_dword v20, v3, s[72:73]
	v_add_u32_e32 v3, s68, v3
	global_load_dword v21, v3, s[72:73]
	v_add_u32_e32 v3, s68, v3
	global_load_dword v22, v3, s[72:73]
	v_add_u32_e32 v3, s68, v3
	global_load_dword v23, v3, s[72:73]
	v_add_u32_e32 v3, s68, v3
	global_load_dword v24, v3, s[72:73]
	v_add_u32_e32 v3, s68, v3
	global_load_dword v25, v3, s[72:73]
	v_add_u32_e32 v3, s68, v3
	global_load_dword v26, v3, s[72:73]
	v_add_u32_e32 v3, s68, v3
	global_load_dword v27, v3, s[72:73]
	v_add_u32_e32 v3, s68, v3
	global_load_dword v28, v3, s[72:73]
	v_add_u32_e32 v3, s68, v3
	global_load_dword v29, v3, s[72:73]
	v_add_u32_e32 v3, s68, v3
	global_load_dword v30, v3, s[72:73]
	v_add_u32_e32 v3, s68, v3
	global_load_dword v31, v3, s[72:73]
	v_add_u32_e32 v3, s68, v3
	global_load_dword v32, v3, s[72:73]
	v_add_u32_e32 v3, s68, v3
	global_load_dword v33, v3, s[72:73]
	v_add_u32_e32 v3, s68, v3
	global_load_dword v34, v3, s[72:73]
	v_add_u32_e32 v3, s68, v3
	global_load_dword v35, v3, s[72:73]
	s_waitcnt vmcnt(0)
	v_permlane32_swap_b32_e32 v4, v20
	v_permlane32_swap_b32_e32 v5, v21
	v_permlane32_swap_b32_e32 v6, v22
	v_permlane32_swap_b32_e32 v7, v23
	v_permlane32_swap_b32_e32 v8, v24
	v_permlane32_swap_b32_e32 v9, v25
	v_permlane32_swap_b32_e32 v10, v26
	v_permlane32_swap_b32_e32 v11, v27
	v_permlane32_swap_b32_e32 v12, v28
	v_permlane32_swap_b32_e32 v13, v29
	v_permlane32_swap_b32_e32 v14, v30
	v_permlane32_swap_b32_e32 v15, v31
	v_permlane32_swap_b32_e32 v16, v32
	v_permlane32_swap_b32_e32 v17, v33
	v_permlane32_swap_b32_e32 v18, v34
	v_permlane32_swap_b32_e32 v19, v35
	v_cvt_pk_bf16_f32 v36, v4, v20
	v_cvt_pk_bf16_f32 v37, v5, v21
	v_cvt_pk_bf16_f32 v38, v6, v22
	v_cvt_pk_bf16_f32 v39, v7, v23
	v_cvt_pk_bf16_f32 v40, v8, v24
	v_cvt_pk_bf16_f32 v41, v9, v25
	v_cvt_pk_bf16_f32 v42, v10, v26
	v_cvt_pk_bf16_f32 v43, v11, v27
	v_cvt_pk_bf16_f32 v44, v12, v28
	v_cvt_pk_bf16_f32 v45, v13, v29
	v_cvt_pk_bf16_f32 v46, v14, v30
	v_cvt_pk_bf16_f32 v47, v15, v31
	v_cvt_pk_bf16_f32 v48, v16, v32
	v_cvt_pk_bf16_f32 v49, v17, v33
	v_cvt_pk_bf16_f32 v50, v18, v34
	v_cvt_pk_bf16_f32 v51, v19, v35
	global_store_dwordx4 v52, v[36:39], s[74:75]
	global_store_dwordx4 v52, v[40:43], s[74:75] offset:16
	global_store_dwordx4 v52, v[44:47], s[74:75] offset:32
	global_store_dwordx4 v52, v[48:51], s[74:75] offset:48
	s_add_u32 s60, s60, s62
	s_branch .Ltr_b_m1_loop
.Ltr_b_m1_end:
	s_load_dwordx2 s[64:65], s[76:77], 0x60
	s_waitcnt lgkmcnt(0)
	s_add_u32 s64, s64, 0x400000
	s_addc_u32 s65, s65, 0
	s_mov_b32 s69, 0x6600000
	s_add_u32 s66, s82, s69
	s_addc_u32 s67, s83, 0
	s_mov_b32 s68, 0x4000
	s_mov_b32 s61, 512
	s_mov_b32 s60, s63
	v_mov_b32_e32 v2, 0x800
	v_mul_u32_u24_e32 v2, v2, v55
	v_add_lshl_u32 v2, v2, v54, 2
	v_mov_b32_e32 v52, 0x400
	v_mul_u32_u24_e32 v52, v52, v54
	v_lshl_add_u32 v52, v55, 6, v52
.Ltr_b_m2_loop:
	s_cmp_ge_u32 s60, s61
	s_cbranch_scc1 .Ltr_b_m2_end
	s_and_b32 s71, s60, 63
	s_lshr_b32 s70, s60, 6
	s_mul_i32 s69, s70, 0x80000
	s_lshl_b32 s80, s71, 7
	s_add_u32 s69, s69, s80
	s_add_u32 s72, s64, s69
	s_addc_u32 s73, s65, 0
	s_mul_i32 s69, s71, 0x8000
	s_lshl_b32 s80, s70, 7
	s_add_u32 s69, s69, s80
	s_add_u32 s74, s66, s69
	s_addc_u32 s75, s67, 0
	v_mov_b32_e32 v3, v2
	global_load_dword v4, v3, s[72:73]
	v_add_u32_e32 v3, s68, v3
	global_load_dword v5, v3, s[72:73]
	v_add_u32_e32 v3, s68, v3
	global_load_dword v6, v3, s[72:73]
	v_add_u32_e32 v3, s68, v3
	global_load_dword v7, v3, s[72:73]
	v_add_u32_e32 v3, s68, v3
	global_load_dword v8, v3, s[72:73]
	v_add_u32_e32 v3, s68, v3
	global_load_dword v9, v3, s[72:73]
	v_add_u32_e32 v3, s68, v3
	global_load_dword v10, v3, s[72:73]
	v_add_u32_e32 v3, s68, v3
	global_load_dword v11, v3, s[72:73]
	v_add_u32_e32 v3, s68, v3
	global_load_dword v12, v3, s[72:73]
	v_add_u32_e32 v3, s68, v3
	global_load_dword v13, v3, s[72:73]
	v_add_u32_e32 v3, s68, v3
	global_load_dword v14, v3, s[72:73]
	v_add_u32_e32 v3, s68, v3
	global_load_dword v15, v3, s[72:73]
	v_add_u32_e32 v3, s68, v3
	global_load_dword v16, v3, s[72:73]
	v_add_u32_e32 v3, s68, v3
	global_load_dword v17, v3, s[72:73]
	v_add_u32_e32 v3, s68, v3
	global_load_dword v18, v3, s[72:73]
	v_add_u32_e32 v3, s68, v3
	global_load_dword v19, v3, s[72:73]
	v_add_u32_e32 v3, s68, v3
	global_load_dword v20, v3, s[72:73]
	v_add_u32_e32 v3, s68, v3
	global_load_dword v21, v3, s[72:73]
	v_add_u32_e32 v3, s68, v3
	global_load_dword v22, v3, s[72:73]
	v_add_u32_e32 v3, s68, v3
	global_load_dword v23, v3, s[72:73]
	v_add_u32_e32 v3, s68, v3
	global_load_dword v24, v3, s[72:73]
	v_add_u32_e32 v3, s68, v3
	global_load_dword v25, v3, s[72:73]
	v_add_u32_e32 v3, s68, v3
	global_load_dword v26, v3, s[72:73]
	v_add_u32_e32 v3, s68, v3
	global_load_dword v27, v3, s[72:73]
	v_add_u32_e32 v3, s68, v3
	global_load_dword v28, v3, s[72:73]
	v_add_u32_e32 v3, s68, v3
	global_load_dword v29, v3, s[72:73]
	v_add_u32_e32 v3, s68, v3
	global_load_dword v30, v3, s[72:73]
	v_add_u32_e32 v3, s68, v3
	global_load_dword v31, v3, s[72:73]
	v_add_u32_e32 v3, s68, v3
	global_load_dword v32, v3, s[72:73]
	v_add_u32_e32 v3, s68, v3
	global_load_dword v33, v3, s[72:73]
	v_add_u32_e32 v3, s68, v3
	global_load_dword v34, v3, s[72:73]
	v_add_u32_e32 v3, s68, v3
	global_load_dword v35, v3, s[72:73]
	s_waitcnt vmcnt(0)
	v_permlane32_swap_b32_e32 v4, v20
	v_permlane32_swap_b32_e32 v5, v21
	v_permlane32_swap_b32_e32 v6, v22
	v_permlane32_swap_b32_e32 v7, v23
	v_permlane32_swap_b32_e32 v8, v24
	v_permlane32_swap_b32_e32 v9, v25
	v_permlane32_swap_b32_e32 v10, v26
	v_permlane32_swap_b32_e32 v11, v27
	v_permlane32_swap_b32_e32 v12, v28
	v_permlane32_swap_b32_e32 v13, v29
	v_permlane32_swap_b32_e32 v14, v30
	v_permlane32_swap_b32_e32 v15, v31
	v_permlane32_swap_b32_e32 v16, v32
	v_permlane32_swap_b32_e32 v17, v33
	v_permlane32_swap_b32_e32 v18, v34
	v_permlane32_swap_b32_e32 v19, v35
	v_cvt_pk_bf16_f32 v36, v4, v20
	v_cvt_pk_bf16_f32 v37, v5, v21
	v_cvt_pk_bf16_f32 v38, v6, v22
	v_cvt_pk_bf16_f32 v39, v7, v23
	v_cvt_pk_bf16_f32 v40, v8, v24
	v_cvt_pk_bf16_f32 v41, v9, v25
	v_cvt_pk_bf16_f32 v42, v10, v26
	v_cvt_pk_bf16_f32 v43, v11, v27
	v_cvt_pk_bf16_f32 v44, v12, v28
	v_cvt_pk_bf16_f32 v45, v13, v29
	v_cvt_pk_bf16_f32 v46, v14, v30
	v_cvt_pk_bf16_f32 v47, v15, v31
	v_cvt_pk_bf16_f32 v48, v16, v32
	v_cvt_pk_bf16_f32 v49, v17, v33
	v_cvt_pk_bf16_f32 v50, v18, v34
	v_cvt_pk_bf16_f32 v51, v19, v35
	global_store_dwordx4 v52, v[36:39], s[74:75]
	global_store_dwordx4 v52, v[40:43], s[74:75] offset:16
	global_store_dwordx4 v52, v[44:47], s[74:75] offset:32
	global_store_dwordx4 v52, v[48:51], s[74:75] offset:48
	s_add_u32 s60, s60, s62
	s_branch .Ltr_b_m2_loop
.Ltr_b_m2_end:
	s_load_dwordx2 s[64:65], s[76:77], 0x98
	s_waitcnt lgkmcnt(0)
	s_add_u32 s64, s64, 0x1000000
	s_addc_u32 s65, s65, 0
	s_mov_b32 s69, 0x6800000
	s_add_u32 s66, s82, s69
	s_addc_u32 s67, s83, 0
	s_mov_b32 s68, 0x4000
	s_mov_b32 s61, 2048
	s_mov_b32 s60, s63
	v_mov_b32_e32 v2, 0x800
	v_mul_u32_u24_e32 v2, v2, v55
	v_add_lshl_u32 v2, v2, v54, 2
	v_mov_b32_e32 v52, 0x1000
	v_mul_u32_u24_e32 v52, v52, v54
	v_lshl_add_u32 v52, v55, 6, v52
.Ltr_b_m3_loop:
	s_cmp_ge_u32 s60, s61
	s_cbranch_scc1 .Ltr_b_m3_end
	s_and_b32 s71, s60, 63
	s_lshr_b32 s70, s60, 6
	s_mul_i32 s69, s70, 0x80000
	s_lshl_b32 s80, s71, 7
	s_add_u32 s69, s69, s80
	s_add_u32 s72, s64, s69
	s_addc_u32 s73, s65, 0
	s_mul_i32 s69, s71, 0x20000
	s_lshl_b32 s80, s70, 7
	s_add_u32 s69, s69, s80
	s_add_u32 s74, s66, s69
	s_addc_u32 s75, s67, 0
	v_mov_b32_e32 v3, v2
	global_load_dword v4, v3, s[72:73]
	v_add_u32_e32 v3, s68, v3
	global_load_dword v5, v3, s[72:73]
	v_add_u32_e32 v3, s68, v3
	global_load_dword v6, v3, s[72:73]
	v_add_u32_e32 v3, s68, v3
	global_load_dword v7, v3, s[72:73]
	v_add_u32_e32 v3, s68, v3
	global_load_dword v8, v3, s[72:73]
	v_add_u32_e32 v3, s68, v3
	global_load_dword v9, v3, s[72:73]
	v_add_u32_e32 v3, s68, v3
	global_load_dword v10, v3, s[72:73]
	v_add_u32_e32 v3, s68, v3
	global_load_dword v11, v3, s[72:73]
	v_add_u32_e32 v3, s68, v3
	global_load_dword v12, v3, s[72:73]
	v_add_u32_e32 v3, s68, v3
	global_load_dword v13, v3, s[72:73]
	v_add_u32_e32 v3, s68, v3
	global_load_dword v14, v3, s[72:73]
	v_add_u32_e32 v3, s68, v3
	global_load_dword v15, v3, s[72:73]
	v_add_u32_e32 v3, s68, v3
	global_load_dword v16, v3, s[72:73]
	v_add_u32_e32 v3, s68, v3
	global_load_dword v17, v3, s[72:73]
	v_add_u32_e32 v3, s68, v3
	global_load_dword v18, v3, s[72:73]
	v_add_u32_e32 v3, s68, v3
	global_load_dword v19, v3, s[72:73]
	v_add_u32_e32 v3, s68, v3
	global_load_dword v20, v3, s[72:73]
	v_add_u32_e32 v3, s68, v3
	global_load_dword v21, v3, s[72:73]
	v_add_u32_e32 v3, s68, v3
	global_load_dword v22, v3, s[72:73]
	v_add_u32_e32 v3, s68, v3
	global_load_dword v23, v3, s[72:73]
	v_add_u32_e32 v3, s68, v3
	global_load_dword v24, v3, s[72:73]
	v_add_u32_e32 v3, s68, v3
	global_load_dword v25, v3, s[72:73]
	v_add_u32_e32 v3, s68, v3
	global_load_dword v26, v3, s[72:73]
	v_add_u32_e32 v3, s68, v3
	global_load_dword v27, v3, s[72:73]
	v_add_u32_e32 v3, s68, v3
	global_load_dword v28, v3, s[72:73]
	v_add_u32_e32 v3, s68, v3
	global_load_dword v29, v3, s[72:73]
	v_add_u32_e32 v3, s68, v3
	global_load_dword v30, v3, s[72:73]
	v_add_u32_e32 v3, s68, v3
	global_load_dword v31, v3, s[72:73]
	v_add_u32_e32 v3, s68, v3
	global_load_dword v32, v3, s[72:73]
	v_add_u32_e32 v3, s68, v3
	global_load_dword v33, v3, s[72:73]
	v_add_u32_e32 v3, s68, v3
	global_load_dword v34, v3, s[72:73]
	v_add_u32_e32 v3, s68, v3
	global_load_dword v35, v3, s[72:73]
	s_waitcnt vmcnt(0)
	v_permlane32_swap_b32_e32 v4, v20
	v_permlane32_swap_b32_e32 v5, v21
	v_permlane32_swap_b32_e32 v6, v22
	v_permlane32_swap_b32_e32 v7, v23
	v_permlane32_swap_b32_e32 v8, v24
	v_permlane32_swap_b32_e32 v9, v25
	v_permlane32_swap_b32_e32 v10, v26
	v_permlane32_swap_b32_e32 v11, v27
	v_permlane32_swap_b32_e32 v12, v28
	v_permlane32_swap_b32_e32 v13, v29
	v_permlane32_swap_b32_e32 v14, v30
	v_permlane32_swap_b32_e32 v15, v31
	v_permlane32_swap_b32_e32 v16, v32
	v_permlane32_swap_b32_e32 v17, v33
	v_permlane32_swap_b32_e32 v18, v34
	v_permlane32_swap_b32_e32 v19, v35
	v_cvt_pk_bf16_f32 v36, v4, v20
	v_cvt_pk_bf16_f32 v37, v5, v21
	v_cvt_pk_bf16_f32 v38, v6, v22
	v_cvt_pk_bf16_f32 v39, v7, v23
	v_cvt_pk_bf16_f32 v40, v8, v24
	v_cvt_pk_bf16_f32 v41, v9, v25
	v_cvt_pk_bf16_f32 v42, v10, v26
	v_cvt_pk_bf16_f32 v43, v11, v27
	v_cvt_pk_bf16_f32 v44, v12, v28
	v_cvt_pk_bf16_f32 v45, v13, v29
	v_cvt_pk_bf16_f32 v46, v14, v30
	v_cvt_pk_bf16_f32 v47, v15, v31
	v_cvt_pk_bf16_f32 v48, v16, v32
	v_cvt_pk_bf16_f32 v49, v17, v33
	v_cvt_pk_bf16_f32 v50, v18, v34
	v_cvt_pk_bf16_f32 v51, v19, v35
	global_store_dwordx4 v52, v[36:39], s[74:75]
	global_store_dwordx4 v52, v[40:43], s[74:75] offset:16
	global_store_dwordx4 v52, v[44:47], s[74:75] offset:32
	global_store_dwordx4 v52, v[48:51], s[74:75] offset:48
	s_add_u32 s60, s60, s62
	s_branch .Ltr_b_m3_loop
